# conv redistribution 12/24 slots (heavy/light)
# speedup vs baseline: 1.0007x; 1.0007x over previous
; __device__ __forceinline__ void conv_phase(bf16_t* proj, const float* cw, int G) {
;     int tid_ = threadIdx.x; asm volatile("" : "+v"(tid_));
;     for (int item = blockIdx.x * 512 + tid_; item < M * 48; item += G * 512) {
;         const int row = item / 48, ch = (item % 48) * 8, t = row % SEQ;
; __device__ __forceinline__ void attn_phase(unsigned char* ws, int l, LAS unsigned char* lds, int G) {
;     ...
;     const int vb = (G % 8 == 0) ? (bx % 8) * (G / 8) + bx / 8 : bx;
.LBB0_561:
	v_mov_b32_e32 v0, v154
	s_lshl_b32 s33, s14, 9
	s_lshl_b32 s95, s14, 9
	s_mov_b32 s93, 0x240000
	s_lshl_b32 s94, s74, 9
	s_cmpk_lg_u32 s74, 0x100
	s_cbranch_scc1 .Lcv0_go
	s_and_b32 s92, s14, 7
	s_lshl_b32 s92, s92, 5
	s_lshr_b32 s95, s14, 3
	s_add_i32 s92, s92, s95
	s_mov_b32 s94, 0x10000
	s_cmpk_lt_u32 s92, 0x80
	s_cbranch_scc1 .Lcv0_heavy
	s_addk_i32 s92, 1408
	s_lshl_b32 s95, s92, 9
	s_branch .Lcv0_go
.Lcv0_heavy:
	s_lshl_b32 s95, s92, 9
	s_mov_b32 s93, 0xc0000

; __device__ __forceinline__ void conv_phase(bf16_t* proj, const float* cw, int G) {
;     int tid_ = threadIdx.x; asm volatile("" : "+v"(tid_));
;     for (int item = blockIdx.x * 512 + tid_; item < M * 48; item += G * 512) {
;         const int row = item / 48, ch = (item % 48) * 8, t = row % SEQ;
; __device__ __forceinline__ void attn_phase(unsigned char* ws, int l, LAS unsigned char* lds, int G) {
;     ...
;     const int vb = (G % 8 == 0) ? (bx % 8) * (G / 8) + bx / 8 : bx;
.LBB0_1273:
	v_mov_b32_e32 v0, v154
	s_lshl_b32 s95, s14, 9
	s_mov_b32 s93, 0x240000
	s_lshl_b32 s94, s74, 9
	s_cmpk_lg_u32 s74, 0x100
	s_cbranch_scc1 .Lcv1_go
	s_and_b32 s92, s14, 7
	s_lshl_b32 s92, s92, 5
	s_lshr_b32 s95, s14, 3
	s_add_i32 s92, s92, s95
	s_mov_b32 s94, 0x10000
	s_cmpk_lt_u32 s92, 0x80
	s_cbranch_scc1 .Lcv1_heavy
	s_addk_i32 s92, 1408
	s_lshl_b32 s95, s92, 9
	s_branch .Lcv1_go
